# adaLN phase task body rewritten by hand (batched loads, pair-interleaved LDS image, software-pipelined weight loads); layer-0 weight conversion in two passes so adaLN blocks join
# speedup vs baseline: 1.0794x; 1.0078x over previous
; __device__ __forceinline__ int otid() { int t = threadIdx.x; asm volatile("" : "+v"(t)); return t; }
; __device__ __forceinline__ void phase_ada(const Params& p, char* smem) {
;   float* sc = (float*)smem;
;   const int tid = otid(), c = tid & 63, kg = tid >> 6;
;   for (int task = blockIdx.x; task < 2 * 144; task += gridDim.x) {
;     const int l = task / 144, n0 = (task % 144) * 64;
;     const float* W = p.in[4] + (size_t)l * 1024 * 9216;
;     float acc[17];
.LBB0_4:
	s_or_b64 exec, exec, s[4:5]
	s_cmpk_gt_i32 s2, 0x11f
	v_mov_b32_e32 v1, v172
	v_writelane_b32 v251, s2, 0
	s_cbranch_scc1 .LBB0_29
	s_load_dwordx2 s[16:17], s[0:1], 0x8
	s_load_dwordx4 s[8:11], s[0:1], 0x18
	s_load_dwordx2 s[18:19], s[0:1], 0x28
	v_ashrrev_i32_e32 v4, 6, v1
	v_and_b32_e32 v52, 63, v1
	v_lshlrev_b32_e32 v2, 7, v4
	s_movk_i32 s6, 0x1100
	s_mov_b32 s31, 0x9000
	v_lshlrev_b32_e32 v53, 2, v52
	v_mul_lo_u32 v5, v4, s6
	v_add_u32_e32 v6, 0x200, v2
	v_mad_i64_i32 v[2:3], s[6:7], v2, s31, 0
	v_or_b32_e32 v2, v2, v53
	s_waitcnt lgkmcnt(0)
	v_lshl_add_u64 v[2:3], s[10:11], 0, v[2:3]
	s_mov_b64 s[6:7], 0x87000
	s_mov_b64 s[4:5], 0x1e2a0000
	v_lshl_add_u64 v[16:17], v[2:3], 0, s[6:7]
	v_mad_i64_i32 v[2:3], s[20:21], v6, s31, 0
	v_lshl_add_u64 v[14:15], v[90:91], 0, s[4:5]
	s_movk_i32 s4, 0x2200
	v_or_b32_e32 v2, v2, v53
	v_cmp_gt_i32_e32 vcc, s4, v1
	s_movk_i32 s4, 0x440
	v_lshl_add_u64 v[2:3], s[10:11], 0, v[2:3]
	v_cmp_gt_i32_e64 s[4:5], s4, v1
	v_lshlrev_b32_e32 v54, 2, v1
	v_lshlrev_b32_e32 v55, 9, v4
	v_lshl_add_u64 v[18:19], v[2:3], 0, s[6:7]
	v_mov_b32_e32 v21, 0
	s_movk_i32 s33, 0x20ff
	s_mov_b32 s34, 0xfff79000
	s_mov_b32 s35, 0xfff82000
	s_mov_b32 s36, 0xfff8b000
	s_mov_b32 s37, 0xfff94000
	s_mov_b32 s50, s2
	s_mov_b32 s38, 0xfff9d000
	s_mov_b32 s39, 0xfffa6000
	s_mov_b32 s40, 0xfffaf000
	s_mov_b32 s41, 0xfffb8000
	s_mov_b32 s42, 0xfffc1000
	s_mov_b32 s43, 0xfffca000
	s_mov_b32 s44, 0xfffd3000
	s_mov_b32 s45, 0xfffdc000
	s_mov_b32 s46, 0xfffe5000
	s_mov_b32 s47, 0xfffee000
	s_mov_b32 s48, 0xffff7000
	s_mov_b64 s[20:21], 0x800
	v_add_u32_e32 v56, v53, v5
	s_movk_i32 s49, 0x33f
	s_branch .LBB0_7

; __device__ __forceinline__ float silu(float x) { return x * sigm(x); }
; __device__ __forceinline__ void phase_ada(const Params& p, char* smem) {
;     ...
;     for (int kh = 0; kh < 2; ++kh) {
;       __syncthreads();
;       for (int i = tid; i < 17 * 512; i += 256) {
;         const int r = i >> 9, k = (i & 511) + kh * 512;
;         const float v = (r < 16) ? p.in[1][r * 1024 + k] : p.in[3][k];
;         sc[i] = silu(v);
;       }
;       __syncthreads();
; #pragma unroll 4
;       for (int kk = 0; kk < 128; kk += 4) {
;         const int kl = kg * 128 + kk;
;         const float* wp = W + (size_t)(kh * 512 + kl) * 9216 + n0 + c;
;         const float w0 = wp[0], w1 = wp[9216], w2 = wp[2 * 9216], w3 = wp[3 * 9216];
.LBB0_7:
	s_mul_hi_i32 s6, s50, 0x38e38e39
	s_lshr_b32 s7, s6, 31
	s_ashr_i32 s51, s6, 5
	s_add_i32 s51, s51, s7
	s_mul_i32 s6, s51, 0x90
	s_sub_i32 s6, s50, s6
	s_lshl_b32 s22, s6, 6
	s_ashr_i32 s23, s22, 31
	s_mul_i32 s24, s51, 0x2400000
	s_lshl_b64 s[6:7], s[22:23], 2
	s_mul_hi_i32 s25, s51, 0x2400000
	s_add_u32 s24, s24, s6
	s_addc_u32 s25, s25, s7
	s_add_u32 s44, s10, s24
	s_addc_u32 s45, s11, s25
	v_lshrrev_b32_e32 v10, 6, v172
	v_mul_u32_u24_e32 v11, 0x480000, v10
	v_add_u32_e32 v11, v11, v53
	v_lshlrev_b32_e32 v12, 3, v172
	v_lshlrev_b32_e32 v13, 10, v10
	v_lshlrev_b32_e32 v10, 9, v10
	v_mov_b32_e32 v22, 0
	v_mov_b32_e32 v23, 0
	v_mov_b32_e32 v24, 0
	v_mov_b32_e32 v25, 0
	v_mov_b32_e32 v26, 0
	v_mov_b32_e32 v27, 0
	v_mov_b32_e32 v30, 0
	v_mov_b32_e32 v31, 0
	v_mov_b32_e32 v32, 0
	v_mov_b32_e32 v33, 0
	v_mov_b32_e32 v34, 0
	v_mov_b32_e32 v35, 0
	v_mov_b32_e32 v36, 0
	v_mov_b32_e32 v37, 0
	v_mov_b32_e32 v38, 0
	v_mov_b32_e32 v39, 0
	v_mov_b32_e32 v50, 0
	s_mov_b32 s26, 0
.Lada_kh:
	s_barrier
	s_lshl_b32 s23, s26, 11
	s_add_u32 s6, s16, s23
	s_addc_u32 s7, s17, 0
	global_load_dword v60, v54, s[6:7]
	global_load_dword v62, v54, s[6:7] offset:1024
	s_add_u32 s6, s6, 0x1000
	s_addc_u32 s7, s7, 0
	global_load_dword v61, v54, s[6:7]
	global_load_dword v63, v54, s[6:7] offset:1024
	s_add_u32 s6, s6, 0x1000
	s_addc_u32 s7, s7, 0
	global_load_dword v64, v54, s[6:7]
	global_load_dword v66, v54, s[6:7] offset:1024
	s_add_u32 s6, s6, 0x1000
	s_addc_u32 s7, s7, 0
	global_load_dword v65, v54, s[6:7]
	global_load_dword v67, v54, s[6:7] offset:1024
	s_add_u32 s6, s6, 0x1000
	s_addc_u32 s7, s7, 0
	global_load_dword v68, v54, s[6:7]
	global_load_dword v70, v54, s[6:7] offset:1024
	s_add_u32 s6, s6, 0x1000
	s_addc_u32 s7, s7, 0
	global_load_dword v69, v54, s[6:7]
	global_load_dword v71, v54, s[6:7] offset:1024
	s_add_u32 s6, s6, 0x1000
	s_addc_u32 s7, s7, 0
	global_load_dword v72, v54, s[6:7]
	global_load_dword v74, v54, s[6:7] offset:1024
	s_add_u32 s6, s6, 0x1000
	s_addc_u32 s7, s7, 0
	global_load_dword v73, v54, s[6:7]
	global_load_dword v75, v54, s[6:7] offset:1024
	s_add_u32 s6, s6, 0x1000
	s_addc_u32 s7, s7, 0
	global_load_dword v76, v54, s[6:7]
	global_load_dword v78, v54, s[6:7] offset:1024
	s_add_u32 s6, s6, 0x1000
	s_addc_u32 s7, s7, 0
	global_load_dword v77, v54, s[6:7]
	global_load_dword v79, v54, s[6:7] offset:1024
	s_add_u32 s6, s6, 0x1000
	s_addc_u32 s7, s7, 0
	global_load_dword v80, v54, s[6:7]
	global_load_dword v82, v54, s[6:7] offset:1024
	s_add_u32 s6, s6, 0x1000
	s_addc_u32 s7, s7, 0
	global_load_dword v81, v54, s[6:7]
	global_load_dword v83, v54, s[6:7] offset:1024
	s_add_u32 s6, s6, 0x1000
	s_addc_u32 s7, s7, 0
	global_load_dword v84, v54, s[6:7]
	global_load_dword v86, v54, s[6:7] offset:1024
	s_add_u32 s6, s6, 0x1000
	s_addc_u32 s7, s7, 0
	global_load_dword v85, v54, s[6:7]
	global_load_dword v87, v54, s[6:7] offset:1024
	s_add_u32 s6, s6, 0x1000
	s_addc_u32 s7, s7, 0
	global_load_dword v88, v54, s[6:7]
	global_load_dword v90, v54, s[6:7] offset:1024
	s_add_u32 s6, s6, 0x1000
	s_addc_u32 s7, s7, 0
	global_load_dword v89, v54, s[6:7]
	global_load_dword v91, v54, s[6:7] offset:1024
	s_add_u32 s6, s6, 0x1000
	s_addc_u32 s7, s7, 0
	s_add_u32 s6, s8, s23
	s_addc_u32 s7, s9, 0
	global_load_dword v92, v54, s[6:7]
	global_load_dword v93, v54, s[6:7] offset:1024
	s_mul_i32 s6, s26, 0x1200000
	s_add_u32 s34, s44, s6
	s_addc_u32 s35, s45, 0
	s_add_u32 s36, s34, 0x9000
	s_addc_u32 s37, s35, 0
	s_add_u32 s38, s36, 0x9000
	s_addc_u32 s39, s37, 0
	s_add_u32 s40, s38, 0x9000
	s_addc_u32 s41, s39, 0
	s_mov_b32 s43, 0x24000
	global_load_dword v200, v11, s[34:35]
	global_load_dword v202, v11, s[36:37]
	global_load_dword v204, v11, s[38:39]
	global_load_dword v206, v11, s[40:41]
	s_add_u32 s34, s34, s43
	s_addc_u32 s35, s35, 0
	s_add_u32 s36, s36, s43
	s_addc_u32 s37, s37, 0
	s_add_u32 s38, s38, s43
	s_addc_u32 s39, s39, 0
	s_add_u32 s40, s40, s43
	s_addc_u32 s41, s41, 0
	global_load_dword v208, v11, s[34:35]
	global_load_dword v210, v11, s[36:37]
	global_load_dword v212, v11, s[38:39]
	global_load_dword v214, v11, s[40:41]
	s_add_u32 s34, s34, s43
	s_addc_u32 s35, s35, 0
	s_add_u32 s36, s36, s43
	s_addc_u32 s37, s37, 0
	s_add_u32 s38, s38, s43
	s_addc_u32 s39, s39, 0
	s_add_u32 s40, s40, s43
	s_addc_u32 s41, s41, 0
	s_waitcnt vmcnt(38)
	v_mul_f32_e32 v2, 0xbfb8aa3b, v60
	v_mul_f32_e32 v3, 0xbfb8aa3b, v61
	v_mul_f32_e32 v4, 0xbfb8aa3b, v62
	v_mul_f32_e32 v5, 0xbfb8aa3b, v63
	v_exp_f32_e32 v2, v2
	v_exp_f32_e32 v3, v3
	v_exp_f32_e32 v4, v4
	v_exp_f32_e32 v5, v5
	v_add_f32_e32 v2, 1.0, v2
	v_add_f32_e32 v3, 1.0, v3
	v_add_f32_e32 v4, 1.0, v4
	v_add_f32_e32 v5, 1.0, v5
	v_rcp_f32_e32 v2, v2
	v_rcp_f32_e32 v3, v3
	v_rcp_f32_e32 v4, v4
	v_rcp_f32_e32 v5, v5
	v_mul_f32_e32 v60, v60, v2
	v_mul_f32_e32 v61, v61, v3
	v_mul_f32_e32 v62, v62, v4
	v_mul_f32_e32 v63, v63, v5
	ds_write_b64 v12, v[60:61] offset:0
	ds_write_b64 v12, v[62:63] offset:2048
	s_waitcnt vmcnt(34)
	v_mul_f32_e32 v2, 0xbfb8aa3b, v64
	v_mul_f32_e32 v3, 0xbfb8aa3b, v65
	v_mul_f32_e32 v4, 0xbfb8aa3b, v66
	v_mul_f32_e32 v5, 0xbfb8aa3b, v67
	v_exp_f32_e32 v2, v2
	v_exp_f32_e32 v3, v3
	v_exp_f32_e32 v4, v4
	v_exp_f32_e32 v5, v5
	v_add_f32_e32 v2, 1.0, v2
	v_add_f32_e32 v3, 1.0, v3
	v_add_f32_e32 v4, 1.0, v4
	v_add_f32_e32 v5, 1.0, v5
	v_rcp_f32_e32 v2, v2
	v_rcp_f32_e32 v3, v3
	v_rcp_f32_e32 v4, v4
	v_rcp_f32_e32 v5, v5
	v_mul_f32_e32 v64, v64, v2
	v_mul_f32_e32 v65, v65, v3
	v_mul_f32_e32 v66, v66, v4
	v_mul_f32_e32 v67, v67, v5
	ds_write_b64 v12, v[64:65] offset:4096
	ds_write_b64 v12, v[66:67] offset:6144
	s_waitcnt vmcnt(30)
; __device__ __forceinline__ float silu(float x) { return x * sigm(x); }
; __device__ __forceinline__ void phase_ada(const Params& p, char* smem) {
;     ...
;       for (int i = tid; i < 17 * 512; i += 256) {
;         const int r = i >> 9, k = (i & 511) + kh * 512;
;         const float v = (r < 16) ? p.in[1][r * 1024 + k] : p.in[3][k];
;         sc[i] = silu(v);
;       }
;       __syncthreads();
; #pragma unroll 4
;       for (int kk = 0; kk < 128; kk += 4) {
;         const int kl = kg * 128 + kk;
;         const float* wp = W + (size_t)(kh * 512 + kl) * 9216 + n0 + c;
;         const float w0 = wp[0], w1 = wp[9216], w2 = wp[2 * 9216], w3 = wp[3 * 9216];
; #pragma unroll
;         for (int r = 0; r < 17; ++r) {
;           const float4 s4 = *(const float4*)(sc + r * 512 + kl);
;           acc[r] += s4.x * w0 + s4.y * w1 + s4.z * w2 + s4.w * w3;
	v_mul_f32_e32 v2, 0xbfb8aa3b, v68
	v_mul_f32_e32 v3, 0xbfb8aa3b, v69
	v_mul_f32_e32 v4, 0xbfb8aa3b, v70
	v_mul_f32_e32 v5, 0xbfb8aa3b, v71
	v_exp_f32_e32 v2, v2
	v_exp_f32_e32 v3, v3
	v_exp_f32_e32 v4, v4
	v_exp_f32_e32 v5, v5
	v_add_f32_e32 v2, 1.0, v2
	v_add_f32_e32 v3, 1.0, v3
	v_add_f32_e32 v4, 1.0, v4
	v_add_f32_e32 v5, 1.0, v5
	v_rcp_f32_e32 v2, v2
	v_rcp_f32_e32 v3, v3
	v_rcp_f32_e32 v4, v4
	v_rcp_f32_e32 v5, v5
	v_mul_f32_e32 v68, v68, v2
	v_mul_f32_e32 v69, v69, v3
	v_mul_f32_e32 v70, v70, v4
	v_mul_f32_e32 v71, v71, v5
	ds_write_b64 v12, v[68:69] offset:8192
	ds_write_b64 v12, v[70:71] offset:10240
	s_waitcnt vmcnt(26)
	v_mul_f32_e32 v2, 0xbfb8aa3b, v72
	v_mul_f32_e32 v3, 0xbfb8aa3b, v73
	v_mul_f32_e32 v4, 0xbfb8aa3b, v74
	v_mul_f32_e32 v5, 0xbfb8aa3b, v75
	v_exp_f32_e32 v2, v2
	v_exp_f32_e32 v3, v3
	v_exp_f32_e32 v4, v4
	v_exp_f32_e32 v5, v5
	v_add_f32_e32 v2, 1.0, v2
	v_add_f32_e32 v3, 1.0, v3
	v_add_f32_e32 v4, 1.0, v4
	v_add_f32_e32 v5, 1.0, v5
	v_rcp_f32_e32 v2, v2
	v_rcp_f32_e32 v3, v3
	v_rcp_f32_e32 v4, v4
	v_rcp_f32_e32 v5, v5
	v_mul_f32_e32 v72, v72, v2
	v_mul_f32_e32 v73, v73, v3
	v_mul_f32_e32 v74, v74, v4
	v_mul_f32_e32 v75, v75, v5
	ds_write_b64 v12, v[72:73] offset:12288
	ds_write_b64 v12, v[74:75] offset:14336
	s_waitcnt vmcnt(22)
	v_mul_f32_e32 v2, 0xbfb8aa3b, v76
	v_mul_f32_e32 v3, 0xbfb8aa3b, v77
	v_mul_f32_e32 v4, 0xbfb8aa3b, v78
	v_mul_f32_e32 v5, 0xbfb8aa3b, v79
	v_exp_f32_e32 v2, v2
	v_exp_f32_e32 v3, v3
	v_exp_f32_e32 v4, v4
	v_exp_f32_e32 v5, v5
	v_add_f32_e32 v2, 1.0, v2
	v_add_f32_e32 v3, 1.0, v3
	v_add_f32_e32 v4, 1.0, v4
	v_add_f32_e32 v5, 1.0, v5
	v_rcp_f32_e32 v2, v2
	v_rcp_f32_e32 v3, v3
	v_rcp_f32_e32 v4, v4
	v_rcp_f32_e32 v5, v5
	v_mul_f32_e32 v76, v76, v2
	v_mul_f32_e32 v77, v77, v3
	v_mul_f32_e32 v78, v78, v4
	v_mul_f32_e32 v79, v79, v5
	ds_write_b64 v12, v[76:77] offset:16384
	ds_write_b64 v12, v[78:79] offset:18432
	s_waitcnt vmcnt(18)
	v_mul_f32_e32 v2, 0xbfb8aa3b, v80
	v_mul_f32_e32 v3, 0xbfb8aa3b, v81
	v_mul_f32_e32 v4, 0xbfb8aa3b, v82
	v_mul_f32_e32 v5, 0xbfb8aa3b, v83
	v_exp_f32_e32 v2, v2
	v_exp_f32_e32 v3, v3
	v_exp_f32_e32 v4, v4
	v_exp_f32_e32 v5, v5
	v_add_f32_e32 v2, 1.0, v2
	v_add_f32_e32 v3, 1.0, v3
	v_add_f32_e32 v4, 1.0, v4
	v_add_f32_e32 v5, 1.0, v5
	v_rcp_f32_e32 v2, v2
	v_rcp_f32_e32 v3, v3
	v_rcp_f32_e32 v4, v4
	v_rcp_f32_e32 v5, v5
	v_mul_f32_e32 v80, v80, v2
	v_mul_f32_e32 v81, v81, v3
	v_mul_f32_e32 v82, v82, v4
	v_mul_f32_e32 v83, v83, v5
	ds_write_b64 v12, v[80:81] offset:20480
	ds_write_b64 v12, v[82:83] offset:22528
	s_waitcnt vmcnt(14)
	v_mul_f32_e32 v2, 0xbfb8aa3b, v84
	v_mul_f32_e32 v3, 0xbfb8aa3b, v85
	v_mul_f32_e32 v4, 0xbfb8aa3b, v86
	v_mul_f32_e32 v5, 0xbfb8aa3b, v87
	v_exp_f32_e32 v2, v2
	v_exp_f32_e32 v3, v3
	v_exp_f32_e32 v4, v4
	v_exp_f32_e32 v5, v5
	v_add_f32_e32 v2, 1.0, v2
	v_add_f32_e32 v3, 1.0, v3
	v_add_f32_e32 v4, 1.0, v4
	v_add_f32_e32 v5, 1.0, v5
	v_rcp_f32_e32 v2, v2
	v_rcp_f32_e32 v3, v3
	v_rcp_f32_e32 v4, v4
	v_rcp_f32_e32 v5, v5
	v_mul_f32_e32 v84, v84, v2
	v_mul_f32_e32 v85, v85, v3
	v_mul_f32_e32 v86, v86, v4
	v_mul_f32_e32 v87, v87, v5
	ds_write_b64 v12, v[84:85] offset:24576
	ds_write_b64 v12, v[86:87] offset:26624
	s_waitcnt vmcnt(10)
	v_mul_f32_e32 v2, 0xbfb8aa3b, v88
	v_mul_f32_e32 v3, 0xbfb8aa3b, v89
	v_mul_f32_e32 v4, 0xbfb8aa3b, v90
	v_mul_f32_e32 v5, 0xbfb8aa3b, v91
	v_exp_f32_e32 v2, v2
	v_exp_f32_e32 v3, v3
	v_exp_f32_e32 v4, v4
	v_exp_f32_e32 v5, v5
	v_add_f32_e32 v2, 1.0, v2
	v_add_f32_e32 v3, 1.0, v3
	v_add_f32_e32 v4, 1.0, v4
	v_add_f32_e32 v5, 1.0, v5
	v_rcp_f32_e32 v2, v2
	v_rcp_f32_e32 v3, v3
	v_rcp_f32_e32 v4, v4
	v_rcp_f32_e32 v5, v5
	v_mul_f32_e32 v88, v88, v2
	v_mul_f32_e32 v89, v89, v3
	v_mul_f32_e32 v90, v90, v4
	v_mul_f32_e32 v91, v91, v5
	ds_write_b64 v12, v[88:89] offset:28672
	ds_write_b64 v12, v[90:91] offset:30720
	s_waitcnt vmcnt(8)
	v_mul_f32_e32 v2, 0xbfb8aa3b, v92
	v_mul_f32_e32 v3, 0xbfb8aa3b, v93
	v_exp_f32_e32 v2, v2
	v_exp_f32_e32 v3, v3
	s_nop 0
	v_add_f32_e32 v2, 1.0, v2
	v_add_f32_e32 v3, 1.0, v3
	v_rcp_f32_e32 v2, v2
	v_rcp_f32_e32 v3, v3
	s_nop 0
	v_mul_f32_e32 v92, v92, v2
	v_mul_f32_e32 v93, v93, v3
	ds_write_b32 v54, v92 offset:32768
	ds_write_b32 v54, v93 offset:33792
	s_waitcnt lgkmcnt(0)
	s_barrier
	ds_read_b128 v[60:63], v13 offset:0
	ds_read_b128 v[64:67], v13 offset:16
	ds_read_b128 v[68:71], v13 offset:4096
	ds_read_b128 v[72:75], v13 offset:4112
	ds_read_b128 v[76:79], v13 offset:8192
	ds_read_b128 v[80:83], v13 offset:8208
	ds_read_b128 v[84:87], v13 offset:12288
	ds_read_b128 v[88:91], v13 offset:12304
	ds_read_b128 v[92:95], v13 offset:16384
	ds_read_b128 v[96:99], v13 offset:16400
	ds_read_b128 v[100:103], v13 offset:20480
	ds_read_b128 v[104:107], v13 offset:20496
	ds_read_b128 v[108:111], v13 offset:24576
	ds_read_b128 v[112:115], v13 offset:24592
	ds_read_b128 v[116:119], v13 offset:28672
	ds_read_b128 v[120:123], v13 offset:28688
	ds_read_b128 v[124:127], v10 offset:32768
	s_mov_b32 s42, 0
	s_mov_b32 s27, 0
; __device__ __forceinline__ void phase_ada(const Params& p, char* smem) {
;     ...
; #pragma unroll 4
;       for (int kk = 0; kk < 128; kk += 4) {
;         const int kl = kg * 128 + kk;
;         const float* wp = W + (size_t)(kh * 512 + kl) * 9216 + n0 + c;
;         const float w0 = wp[0], w1 = wp[9216], w2 = wp[2 * 9216], w3 = wp[3 * 9216];
; #pragma unroll
;         for (int r = 0; r < 17; ++r) {
;           const float4 s4 = *(const float4*)(sc + r * 512 + kl);
;           acc[r] += s4.x * w0 + s4.y * w1 + s4.z * w2 + s4.w * w3;
;         }
;       }
.Lada_k:
	s_cmp_lt_u32 s42, 29
	s_cselect_b32 s43, 0x24000, 0
	global_load_dword v216, v11, s[34:35]
	global_load_dword v218, v11, s[36:37]
	global_load_dword v220, v11, s[38:39]
	global_load_dword v222, v11, s[40:41]
	s_add_u32 s34, s34, s43
	s_addc_u32 s35, s35, 0
	s_add_u32 s36, s36, s43
	s_addc_u32 s37, s37, 0
	s_add_u32 s38, s38, s43
	s_addc_u32 s39, s39, 0
	s_add_u32 s40, s40, s43
	s_addc_u32 s41, s41, 0
	s_add_i32 s42, s42, 1
	s_waitcnt lgkmcnt(0)
	ds_read_b128 v[128:131], v13 offset:32
	ds_read_b128 v[132:135], v13 offset:48
	ds_read_b128 v[136:139], v13 offset:4128
	ds_read_b128 v[140:143], v13 offset:4144
	ds_read_b128 v[144:147], v13 offset:8224
	ds_read_b128 v[148:151], v13 offset:8240
	ds_read_b128 v[152:155], v13 offset:12320
	ds_read_b128 v[156:159], v13 offset:12336
	ds_read_b128 v[160:163], v13 offset:16416
	ds_read_b128 v[164:167], v13 offset:16432
	ds_read_b128 v[168:171], v13 offset:20512
	ds_read_b128 v[176:179], v13 offset:20528
	ds_read_b128 v[180:183], v13 offset:24608
	ds_read_b128 v[184:187], v13 offset:24624
	ds_read_b128 v[188:191], v13 offset:28704
	ds_read_b128 v[192:195], v13 offset:28720
	ds_read_b128 v[196:199], v10 offset:32784
	s_waitcnt vmcnt(8)
	v_pk_mul_f32 v[2:3], v[202:203], v[62:63] op_sel_hi:[0,1]
	v_pk_fma_f32 v[2:3], v[200:201], v[60:61], v[2:3] op_sel_hi:[0,1,1]
	v_pk_fma_f32 v[2:3], v[204:205], v[64:65], v[2:3] op_sel_hi:[0,1,1]
	v_pk_fma_f32 v[2:3], v[206:207], v[66:67], v[2:3] op_sel_hi:[0,1,1]
	v_pk_add_f32 v[22:23], v[22:23], v[2:3]
	v_pk_mul_f32 v[4:5], v[202:203], v[70:71] op_sel_hi:[0,1]
	v_pk_fma_f32 v[4:5], v[200:201], v[68:69], v[4:5] op_sel_hi:[0,1,1]
	v_pk_fma_f32 v[4:5], v[204:205], v[72:73], v[4:5] op_sel_hi:[0,1,1]
	v_pk_fma_f32 v[4:5], v[206:207], v[74:75], v[4:5] op_sel_hi:[0,1,1]
	v_pk_add_f32 v[24:25], v[24:25], v[4:5]
	v_pk_mul_f32 v[6:7], v[202:203], v[78:79] op_sel_hi:[0,1]
	v_pk_fma_f32 v[6:7], v[200:201], v[76:77], v[6:7] op_sel_hi:[0,1,1]
	v_pk_fma_f32 v[6:7], v[204:205], v[80:81], v[6:7] op_sel_hi:[0,1,1]
	v_pk_fma_f32 v[6:7], v[206:207], v[82:83], v[6:7] op_sel_hi:[0,1,1]
	v_pk_add_f32 v[26:27], v[26:27], v[6:7]
	v_pk_mul_f32 v[8:9], v[202:203], v[86:87] op_sel_hi:[0,1]
	v_pk_fma_f32 v[8:9], v[200:201], v[84:85], v[8:9] op_sel_hi:[0,1,1]
	v_pk_fma_f32 v[8:9], v[204:205], v[88:89], v[8:9] op_sel_hi:[0,1,1]
	v_pk_fma_f32 v[8:9], v[206:207], v[90:91], v[8:9] op_sel_hi:[0,1,1]
	v_pk_add_f32 v[30:31], v[30:31], v[8:9]
	v_pk_mul_f32 v[2:3], v[202:203], v[94:95] op_sel_hi:[0,1]
	v_pk_fma_f32 v[2:3], v[200:201], v[92:93], v[2:3] op_sel_hi:[0,1,1]
	v_pk_fma_f32 v[2:3], v[204:205], v[96:97], v[2:3] op_sel_hi:[0,1,1]
	v_pk_fma_f32 v[2:3], v[206:207], v[98:99], v[2:3] op_sel_hi:[0,1,1]
	v_pk_add_f32 v[32:33], v[32:33], v[2:3]
	v_pk_mul_f32 v[4:5], v[202:203], v[102:103] op_sel_hi:[0,1]
	v_pk_fma_f32 v[4:5], v[200:201], v[100:101], v[4:5] op_sel_hi:[0,1,1]
	v_pk_fma_f32 v[4:5], v[204:205], v[104:105], v[4:5] op_sel_hi:[0,1,1]
	v_pk_fma_f32 v[4:5], v[206:207], v[106:107], v[4:5] op_sel_hi:[0,1,1]
	v_pk_add_f32 v[34:35], v[34:35], v[4:5]
	v_pk_mul_f32 v[6:7], v[202:203], v[110:111] op_sel_hi:[0,1]
	v_pk_fma_f32 v[6:7], v[200:201], v[108:109], v[6:7] op_sel_hi:[0,1,1]
	v_pk_fma_f32 v[6:7], v[204:205], v[112:113], v[6:7] op_sel_hi:[0,1,1]
	v_pk_fma_f32 v[6:7], v[206:207], v[114:115], v[6:7] op_sel_hi:[0,1,1]
	v_pk_add_f32 v[36:37], v[36:37], v[6:7]
	v_pk_mul_f32 v[8:9], v[202:203], v[118:119] op_sel_hi:[0,1]
	v_pk_fma_f32 v[8:9], v[200:201], v[116:117], v[8:9] op_sel_hi:[0,1,1]
	v_pk_fma_f32 v[8:9], v[204:205], v[120:121], v[8:9] op_sel_hi:[0,1,1]
	v_pk_fma_f32 v[8:9], v[206:207], v[122:123], v[8:9] op_sel_hi:[0,1,1]
	v_pk_add_f32 v[38:39], v[38:39], v[8:9]
	v_mul_f32_e32 v2, v200, v124
	v_mul_f32_e32 v3, v202, v125
	v_mul_f32_e32 v4, v204, v126
	v_mul_f32_e32 v5, v206, v127
	v_add_f32_e32 v2, v2, v3
	v_add_f32_e32 v2, v2, v4
	v_add_f32_e32 v2, v2, v5
	v_add_f32_e32 v50, v50, v2
	s_cmp_lt_u32 s42, 29
	s_cselect_b32 s43, 0x24000, 0
	global_load_dword v224, v11, s[34:35]
	global_load_dword v226, v11, s[36:37]
	global_load_dword v228, v11, s[38:39]
	global_load_dword v230, v11, s[40:41]
	s_add_u32 s34, s34, s43
	s_addc_u32 s35, s35, 0
	s_add_u32 s36, s36, s43
	s_addc_u32 s37, s37, 0
	s_add_u32 s38, s38, s43
	s_addc_u32 s39, s39, 0
	s_add_u32 s40, s40, s43
	s_addc_u32 s41, s41, 0
	s_add_i32 s42, s42, 1
	s_waitcnt lgkmcnt(0)
	ds_read_b128 v[60:63], v13 offset:64
	ds_read_b128 v[64:67], v13 offset:80
	ds_read_b128 v[68:71], v13 offset:4160
	ds_read_b128 v[72:75], v13 offset:4176
	ds_read_b128 v[76:79], v13 offset:8256
	ds_read_b128 v[80:83], v13 offset:8272
	ds_read_b128 v[84:87], v13 offset:12352
	ds_read_b128 v[88:91], v13 offset:12368
	ds_read_b128 v[92:95], v13 offset:16448
	ds_read_b128 v[96:99], v13 offset:16464
	ds_read_b128 v[100:103], v13 offset:20544
	ds_read_b128 v[104:107], v13 offset:20560
	ds_read_b128 v[108:111], v13 offset:24640
	ds_read_b128 v[112:115], v13 offset:24656
	ds_read_b128 v[116:119], v13 offset:28736
	ds_read_b128 v[120:123], v13 offset:28752
	ds_read_b128 v[124:127], v10 offset:32800
	s_waitcnt vmcnt(8)
; __device__ __forceinline__ void phase_ada(const Params& p, char* smem) {
;     ...
; #pragma unroll 4
;       for (int kk = 0; kk < 128; kk += 4) {
;         const int kl = kg * 128 + kk;
;         const float* wp = W + (size_t)(kh * 512 + kl) * 9216 + n0 + c;
;         const float w0 = wp[0], w1 = wp[9216], w2 = wp[2 * 9216], w3 = wp[3 * 9216];
; #pragma unroll
;         for (int r = 0; r < 17; ++r) {
;           const float4 s4 = *(const float4*)(sc + r * 512 + kl);
;           acc[r] += s4.x * w0 + s4.y * w1 + s4.z * w2 + s4.w * w3;
;         }
;       }
	v_pk_mul_f32 v[2:3], v[210:211], v[130:131] op_sel_hi:[0,1]
	v_pk_fma_f32 v[2:3], v[208:209], v[128:129], v[2:3] op_sel_hi:[0,1,1]
	v_pk_fma_f32 v[2:3], v[212:213], v[132:133], v[2:3] op_sel_hi:[0,1,1]
	v_pk_fma_f32 v[2:3], v[214:215], v[134:135], v[2:3] op_sel_hi:[0,1,1]
	v_pk_add_f32 v[22:23], v[22:23], v[2:3]
	v_pk_mul_f32 v[4:5], v[210:211], v[138:139] op_sel_hi:[0,1]
	v_pk_fma_f32 v[4:5], v[208:209], v[136:137], v[4:5] op_sel_hi:[0,1,1]
	v_pk_fma_f32 v[4:5], v[212:213], v[140:141], v[4:5] op_sel_hi:[0,1,1]
	v_pk_fma_f32 v[4:5], v[214:215], v[142:143], v[4:5] op_sel_hi:[0,1,1]
	v_pk_add_f32 v[24:25], v[24:25], v[4:5]
	v_pk_mul_f32 v[6:7], v[210:211], v[146:147] op_sel_hi:[0,1]
	v_pk_fma_f32 v[6:7], v[208:209], v[144:145], v[6:7] op_sel_hi:[0,1,1]
	v_pk_fma_f32 v[6:7], v[212:213], v[148:149], v[6:7] op_sel_hi:[0,1,1]
	v_pk_fma_f32 v[6:7], v[214:215], v[150:151], v[6:7] op_sel_hi:[0,1,1]
	v_pk_add_f32 v[26:27], v[26:27], v[6:7]
	v_pk_mul_f32 v[8:9], v[210:211], v[154:155] op_sel_hi:[0,1]
	v_pk_fma_f32 v[8:9], v[208:209], v[152:153], v[8:9] op_sel_hi:[0,1,1]
	v_pk_fma_f32 v[8:9], v[212:213], v[156:157], v[8:9] op_sel_hi:[0,1,1]
	v_pk_fma_f32 v[8:9], v[214:215], v[158:159], v[8:9] op_sel_hi:[0,1,1]
	v_pk_add_f32 v[30:31], v[30:31], v[8:9]
	v_pk_mul_f32 v[2:3], v[210:211], v[162:163] op_sel_hi:[0,1]
	v_pk_fma_f32 v[2:3], v[208:209], v[160:161], v[2:3] op_sel_hi:[0,1,1]
	v_pk_fma_f32 v[2:3], v[212:213], v[164:165], v[2:3] op_sel_hi:[0,1,1]
	v_pk_fma_f32 v[2:3], v[214:215], v[166:167], v[2:3] op_sel_hi:[0,1,1]
	v_pk_add_f32 v[32:33], v[32:33], v[2:3]
	v_pk_mul_f32 v[4:5], v[210:211], v[170:171] op_sel_hi:[0,1]
	v_pk_fma_f32 v[4:5], v[208:209], v[168:169], v[4:5] op_sel_hi:[0,1,1]
	v_pk_fma_f32 v[4:5], v[212:213], v[176:177], v[4:5] op_sel_hi:[0,1,1]
	v_pk_fma_f32 v[4:5], v[214:215], v[178:179], v[4:5] op_sel_hi:[0,1,1]
	v_pk_add_f32 v[34:35], v[34:35], v[4:5]
	v_pk_mul_f32 v[6:7], v[210:211], v[182:183] op_sel_hi:[0,1]
	v_pk_fma_f32 v[6:7], v[208:209], v[180:181], v[6:7] op_sel_hi:[0,1,1]
	v_pk_fma_f32 v[6:7], v[212:213], v[184:185], v[6:7] op_sel_hi:[0,1,1]
	v_pk_fma_f32 v[6:7], v[214:215], v[186:187], v[6:7] op_sel_hi:[0,1,1]
	v_pk_add_f32 v[36:37], v[36:37], v[6:7]
	v_pk_mul_f32 v[8:9], v[210:211], v[190:191] op_sel_hi:[0,1]
	v_pk_fma_f32 v[8:9], v[208:209], v[188:189], v[8:9] op_sel_hi:[0,1,1]
	v_pk_fma_f32 v[8:9], v[212:213], v[192:193], v[8:9] op_sel_hi:[0,1,1]
	v_pk_fma_f32 v[8:9], v[214:215], v[194:195], v[8:9] op_sel_hi:[0,1,1]
	v_pk_add_f32 v[38:39], v[38:39], v[8:9]
	v_mul_f32_e32 v2, v208, v196
	v_mul_f32_e32 v3, v210, v197
	v_mul_f32_e32 v4, v212, v198
	v_mul_f32_e32 v5, v214, v199
	v_add_f32_e32 v2, v2, v3
	v_add_f32_e32 v2, v2, v4
	v_add_f32_e32 v2, v2, v5
	v_add_f32_e32 v50, v50, v2
	s_cmp_lt_u32 s42, 29
	s_cselect_b32 s43, 0x24000, 0
	global_load_dword v200, v11, s[34:35]
	global_load_dword v202, v11, s[36:37]
	global_load_dword v204, v11, s[38:39]
	global_load_dword v206, v11, s[40:41]
	s_add_u32 s34, s34, s43
	s_addc_u32 s35, s35, 0
	s_add_u32 s36, s36, s43
	s_addc_u32 s37, s37, 0
	s_add_u32 s38, s38, s43
	s_addc_u32 s39, s39, 0
	s_add_u32 s40, s40, s43
	s_addc_u32 s41, s41, 0
	s_add_i32 s42, s42, 1
	s_waitcnt lgkmcnt(0)
	ds_read_b128 v[128:131], v13 offset:96
	ds_read_b128 v[132:135], v13 offset:112
	ds_read_b128 v[136:139], v13 offset:4192
	ds_read_b128 v[140:143], v13 offset:4208
	ds_read_b128 v[144:147], v13 offset:8288
	ds_read_b128 v[148:151], v13 offset:8304
	ds_read_b128 v[152:155], v13 offset:12384
	ds_read_b128 v[156:159], v13 offset:12400
	ds_read_b128 v[160:163], v13 offset:16480
	ds_read_b128 v[164:167], v13 offset:16496
	ds_read_b128 v[168:171], v13 offset:20576
	ds_read_b128 v[176:179], v13 offset:20592
	ds_read_b128 v[180:183], v13 offset:24672
	ds_read_b128 v[184:187], v13 offset:24688
	ds_read_b128 v[188:191], v13 offset:28768
	ds_read_b128 v[192:195], v13 offset:28784
	ds_read_b128 v[196:199], v10 offset:32816
	s_waitcnt vmcnt(8)
	v_pk_mul_f32 v[2:3], v[218:219], v[62:63] op_sel_hi:[0,1]
	v_pk_fma_f32 v[2:3], v[216:217], v[60:61], v[2:3] op_sel_hi:[0,1,1]
	v_pk_fma_f32 v[2:3], v[220:221], v[64:65], v[2:3] op_sel_hi:[0,1,1]
	v_pk_fma_f32 v[2:3], v[222:223], v[66:67], v[2:3] op_sel_hi:[0,1,1]
	v_pk_add_f32 v[22:23], v[22:23], v[2:3]
	v_pk_mul_f32 v[4:5], v[218:219], v[70:71] op_sel_hi:[0,1]
	v_pk_fma_f32 v[4:5], v[216:217], v[68:69], v[4:5] op_sel_hi:[0,1,1]
	v_pk_fma_f32 v[4:5], v[220:221], v[72:73], v[4:5] op_sel_hi:[0,1,1]
	v_pk_fma_f32 v[4:5], v[222:223], v[74:75], v[4:5] op_sel_hi:[0,1,1]
	v_pk_add_f32 v[24:25], v[24:25], v[4:5]
	v_pk_mul_f32 v[6:7], v[218:219], v[78:79] op_sel_hi:[0,1]
	v_pk_fma_f32 v[6:7], v[216:217], v[76:77], v[6:7] op_sel_hi:[0,1,1]
	v_pk_fma_f32 v[6:7], v[220:221], v[80:81], v[6:7] op_sel_hi:[0,1,1]
	v_pk_fma_f32 v[6:7], v[222:223], v[82:83], v[6:7] op_sel_hi:[0,1,1]
	v_pk_add_f32 v[26:27], v[26:27], v[6:7]
	v_pk_mul_f32 v[8:9], v[218:219], v[86:87] op_sel_hi:[0,1]
	v_pk_fma_f32 v[8:9], v[216:217], v[84:85], v[8:9] op_sel_hi:[0,1,1]
	v_pk_fma_f32 v[8:9], v[220:221], v[88:89], v[8:9] op_sel_hi:[0,1,1]
	v_pk_fma_f32 v[8:9], v[222:223], v[90:91], v[8:9] op_sel_hi:[0,1,1]
	v_pk_add_f32 v[30:31], v[30:31], v[8:9]
	v_pk_mul_f32 v[2:3], v[218:219], v[94:95] op_sel_hi:[0,1]
	v_pk_fma_f32 v[2:3], v[216:217], v[92:93], v[2:3] op_sel_hi:[0,1,1]
	v_pk_fma_f32 v[2:3], v[220:221], v[96:97], v[2:3] op_sel_hi:[0,1,1]
	v_pk_fma_f32 v[2:3], v[222:223], v[98:99], v[2:3] op_sel_hi:[0,1,1]
	v_pk_add_f32 v[32:33], v[32:33], v[2:3]
	v_pk_mul_f32 v[4:5], v[218:219], v[102:103] op_sel_hi:[0,1]
	v_pk_fma_f32 v[4:5], v[216:217], v[100:101], v[4:5] op_sel_hi:[0,1,1]
; __device__ __forceinline__ void phase_ada(const Params& p, char* smem) {
;     ...
; #pragma unroll 4
;       for (int kk = 0; kk < 128; kk += 4) {
;         const int kl = kg * 128 + kk;
;         const float* wp = W + (size_t)(kh * 512 + kl) * 9216 + n0 + c;
;         const float w0 = wp[0], w1 = wp[9216], w2 = wp[2 * 9216], w3 = wp[3 * 9216];
; #pragma unroll
;         for (int r = 0; r < 17; ++r) {
;           const float4 s4 = *(const float4*)(sc + r * 512 + kl);
;           acc[r] += s4.x * w0 + s4.y * w1 + s4.z * w2 + s4.w * w3;
;         }
;       }
;     }
;     __syncthreads();
; #pragma unroll
;     for (int r = 0; r < 17; ++r) sc[(kg * 17 + r) * 64 + c] = acc[r];
;     __syncthreads();
	v_pk_fma_f32 v[4:5], v[220:221], v[104:105], v[4:5] op_sel_hi:[0,1,1]
	v_pk_fma_f32 v[4:5], v[222:223], v[106:107], v[4:5] op_sel_hi:[0,1,1]
	v_pk_add_f32 v[34:35], v[34:35], v[4:5]
	v_pk_mul_f32 v[6:7], v[218:219], v[110:111] op_sel_hi:[0,1]
	v_pk_fma_f32 v[6:7], v[216:217], v[108:109], v[6:7] op_sel_hi:[0,1,1]
	v_pk_fma_f32 v[6:7], v[220:221], v[112:113], v[6:7] op_sel_hi:[0,1,1]
	v_pk_fma_f32 v[6:7], v[222:223], v[114:115], v[6:7] op_sel_hi:[0,1,1]
	v_pk_add_f32 v[36:37], v[36:37], v[6:7]
	v_pk_mul_f32 v[8:9], v[218:219], v[118:119] op_sel_hi:[0,1]
	v_pk_fma_f32 v[8:9], v[216:217], v[116:117], v[8:9] op_sel_hi:[0,1,1]
	v_pk_fma_f32 v[8:9], v[220:221], v[120:121], v[8:9] op_sel_hi:[0,1,1]
	v_pk_fma_f32 v[8:9], v[222:223], v[122:123], v[8:9] op_sel_hi:[0,1,1]
	v_pk_add_f32 v[38:39], v[38:39], v[8:9]
	v_mul_f32_e32 v2, v216, v124
	v_mul_f32_e32 v3, v218, v125
	v_mul_f32_e32 v4, v220, v126
	v_mul_f32_e32 v5, v222, v127
	v_add_f32_e32 v2, v2, v3
	v_add_f32_e32 v2, v2, v4
	v_add_f32_e32 v2, v2, v5
	v_add_f32_e32 v50, v50, v2
	s_cmp_lt_u32 s42, 29
	s_cselect_b32 s43, 0x24000, 0
	global_load_dword v208, v11, s[34:35]
	global_load_dword v210, v11, s[36:37]
	global_load_dword v212, v11, s[38:39]
	global_load_dword v214, v11, s[40:41]
	s_add_u32 s34, s34, s43
	s_addc_u32 s35, s35, 0
	s_add_u32 s36, s36, s43
	s_addc_u32 s37, s37, 0
	s_add_u32 s38, s38, s43
	s_addc_u32 s39, s39, 0
	s_add_u32 s40, s40, s43
	s_addc_u32 s41, s41, 0
	s_add_i32 s42, s42, 1
	s_waitcnt lgkmcnt(0)
	ds_read_b128 v[60:63], v13 offset:128
	ds_read_b128 v[64:67], v13 offset:144
	ds_read_b128 v[68:71], v13 offset:4224
	ds_read_b128 v[72:75], v13 offset:4240
	ds_read_b128 v[76:79], v13 offset:8320
	ds_read_b128 v[80:83], v13 offset:8336
	ds_read_b128 v[84:87], v13 offset:12416
	ds_read_b128 v[88:91], v13 offset:12432
	ds_read_b128 v[92:95], v13 offset:16512
	ds_read_b128 v[96:99], v13 offset:16528
	ds_read_b128 v[100:103], v13 offset:20608
	ds_read_b128 v[104:107], v13 offset:20624
	ds_read_b128 v[108:111], v13 offset:24704
	ds_read_b128 v[112:115], v13 offset:24720
	ds_read_b128 v[116:119], v13 offset:28800
	ds_read_b128 v[120:123], v13 offset:28816
	ds_read_b128 v[124:127], v10 offset:32832
	s_waitcnt vmcnt(8)
	v_pk_mul_f32 v[2:3], v[226:227], v[130:131] op_sel_hi:[0,1]
	v_pk_fma_f32 v[2:3], v[224:225], v[128:129], v[2:3] op_sel_hi:[0,1,1]
	v_pk_fma_f32 v[2:3], v[228:229], v[132:133], v[2:3] op_sel_hi:[0,1,1]
	v_pk_fma_f32 v[2:3], v[230:231], v[134:135], v[2:3] op_sel_hi:[0,1,1]
	v_pk_add_f32 v[22:23], v[22:23], v[2:3]
	v_pk_mul_f32 v[4:5], v[226:227], v[138:139] op_sel_hi:[0,1]
	v_pk_fma_f32 v[4:5], v[224:225], v[136:137], v[4:5] op_sel_hi:[0,1,1]
	v_pk_fma_f32 v[4:5], v[228:229], v[140:141], v[4:5] op_sel_hi:[0,1,1]
	v_pk_fma_f32 v[4:5], v[230:231], v[142:143], v[4:5] op_sel_hi:[0,1,1]
	v_pk_add_f32 v[24:25], v[24:25], v[4:5]
	v_pk_mul_f32 v[6:7], v[226:227], v[146:147] op_sel_hi:[0,1]
	v_pk_fma_f32 v[6:7], v[224:225], v[144:145], v[6:7] op_sel_hi:[0,1,1]
	v_pk_fma_f32 v[6:7], v[228:229], v[148:149], v[6:7] op_sel_hi:[0,1,1]
	v_pk_fma_f32 v[6:7], v[230:231], v[150:151], v[6:7] op_sel_hi:[0,1,1]
	v_pk_add_f32 v[26:27], v[26:27], v[6:7]
	v_pk_mul_f32 v[8:9], v[226:227], v[154:155] op_sel_hi:[0,1]
	v_pk_fma_f32 v[8:9], v[224:225], v[152:153], v[8:9] op_sel_hi:[0,1,1]
	v_pk_fma_f32 v[8:9], v[228:229], v[156:157], v[8:9] op_sel_hi:[0,1,1]
	v_pk_fma_f32 v[8:9], v[230:231], v[158:159], v[8:9] op_sel_hi:[0,1,1]
	v_pk_add_f32 v[30:31], v[30:31], v[8:9]
	v_pk_mul_f32 v[2:3], v[226:227], v[162:163] op_sel_hi:[0,1]
	v_pk_fma_f32 v[2:3], v[224:225], v[160:161], v[2:3] op_sel_hi:[0,1,1]
	v_pk_fma_f32 v[2:3], v[228:229], v[164:165], v[2:3] op_sel_hi:[0,1,1]
	v_pk_fma_f32 v[2:3], v[230:231], v[166:167], v[2:3] op_sel_hi:[0,1,1]
	v_pk_add_f32 v[32:33], v[32:33], v[2:3]
	v_pk_mul_f32 v[4:5], v[226:227], v[170:171] op_sel_hi:[0,1]
	v_pk_fma_f32 v[4:5], v[224:225], v[168:169], v[4:5] op_sel_hi:[0,1,1]
	v_pk_fma_f32 v[4:5], v[228:229], v[176:177], v[4:5] op_sel_hi:[0,1,1]
	v_pk_fma_f32 v[4:5], v[230:231], v[178:179], v[4:5] op_sel_hi:[0,1,1]
	v_pk_add_f32 v[34:35], v[34:35], v[4:5]
	v_pk_mul_f32 v[6:7], v[226:227], v[182:183] op_sel_hi:[0,1]
	v_pk_fma_f32 v[6:7], v[224:225], v[180:181], v[6:7] op_sel_hi:[0,1,1]
	v_pk_fma_f32 v[6:7], v[228:229], v[184:185], v[6:7] op_sel_hi:[0,1,1]
	v_pk_fma_f32 v[6:7], v[230:231], v[186:187], v[6:7] op_sel_hi:[0,1,1]
	v_pk_add_f32 v[36:37], v[36:37], v[6:7]
	v_pk_mul_f32 v[8:9], v[226:227], v[190:191] op_sel_hi:[0,1]
	v_pk_fma_f32 v[8:9], v[224:225], v[188:189], v[8:9] op_sel_hi:[0,1,1]
	v_pk_fma_f32 v[8:9], v[228:229], v[192:193], v[8:9] op_sel_hi:[0,1,1]
	v_pk_fma_f32 v[8:9], v[230:231], v[194:195], v[8:9] op_sel_hi:[0,1,1]
	v_pk_add_f32 v[38:39], v[38:39], v[8:9]
	v_mul_f32_e32 v2, v224, v196
	v_mul_f32_e32 v3, v226, v197
	v_mul_f32_e32 v4, v228, v198
	v_mul_f32_e32 v5, v230, v199
	v_add_f32_e32 v2, v2, v3
	v_add_f32_e32 v2, v2, v4
	v_add_f32_e32 v2, v2, v5
	v_add_f32_e32 v50, v50, v2
	v_add_u32_e32 v13, 0x80, v13
	v_add_u32_e32 v10, 64, v10
	s_add_i32 s27, s27, 1
	s_cmp_lt_u32 s27, 8
	s_cbranch_scc1 .Lada_k
	s_waitcnt vmcnt(0) lgkmcnt(0)
	v_subrev_u32_e32 v13, 0x400, v13
	v_subrev_u32_e32 v10, 0x200, v10
	s_add_i32 s26, s26, 1
	s_cmp_lt_u32 s26, 2
	s_cbranch_scc1 .Lada_kh
	s_barrier
	ds_write2st64_b32 v56, v22, v23 offset1:1
	ds_write2st64_b32 v56, v24, v25 offset0:2 offset1:3
	ds_write2st64_b32 v56, v26, v27 offset0:4 offset1:5
	ds_write2st64_b32 v56, v30, v31 offset0:6 offset1:7
	ds_write2st64_b32 v56, v32, v33 offset0:8 offset1:9
	ds_write2st64_b32 v56, v34, v35 offset0:10 offset1:11
	ds_write2st64_b32 v56, v36, v37 offset0:12 offset1:13
	ds_write2st64_b32 v56, v38, v39 offset0:14 offset1:15
	ds_write_b32 v56, v50 offset:4096
	s_waitcnt lgkmcnt(0)
	s_barrier
	s_and_saveexec_b64 s[24:25], s[4:5]
	s_cbranch_execz .LBB0_6
	s_mul_i32 s6, s51, 0x2400
	v_or_b32_e32 v4, s22, v52
	v_add_u32_e32 v2, s6, v4
	v_ashrrev_i32_e32 v3, 31, v2
	v_ashrrev_i32_e32 v5, 31, v4
	s_mul_i32 s51, s51, 17
	v_lshl_add_u64 v[2:3], v[2:3], 2, s[18:19]
	v_lshl_add_u64 v[4:5], v[4:5], 2, v[14:15]
	s_mov_b64 s[22:23], 0
	v_mov_b32_e32 v6, v1

; __device__ __forceinline__ void phase_cvt(const Params& p, int l, char* smem) {
;   const int total = p.job_tiles[l];
;   for (int t = blockIdx.x; t < total; t += gridDim.x) {
;     int ji = 0;
; #pragma unroll 1
;     for (int q = 1; q < 15; ++q) if (t >= p.jobs[l * 15 + q].tile0) ji = q;
;     const CvtJob& j = p.jobs[l * 15 + ji];
;     cvt_tile(j, t - j.tile0, smem);
;   }
; }
.LBB0_32:
	s_cmp_gt_u32 s91, 13
	s_cselect_b64 s[28:29], -1, 0
	s_and_b64 s[22:23], s[28:29], exec
	s_cselect_b32 s77, -14, 0
	s_add_i32 s77, s77, s91
	s_cmp_lg_u32 s77, 0
	s_cselect_b64 s[22:23], -1, 0
	v_writelane_b32 v250, s22, 31
	s_and_b64 vcc, exec, s[22:23]
	s_nop 0
	v_writelane_b32 v250, s23, 32
	s_cbranch_vccnz .LBB0_62
	v_cndmask_b32_e64 v0, 0, 1, s[28:29]
	s_nop 0
	v_readfirstlane_b32 s22, v0
	s_lshl_b32 s22, s22, 2
	s_load_dword s22, s[0:1], s22 offset:0x6a8
	s_waitcnt lgkmcnt(0)
	s_mov_b32 s100, s3
	s_mov_b32 s101, s2
	s_cmp_gt_u32 s91, 13
	s_cbranch_scc1 .Lcvt_all
	s_cmpk_lt_u32 s3, 0x180
	s_cbranch_scc1 .Lcvt_all
	s_cmpk_lt_u32 s2, 0x120
	s_cbranch_scc1 .Lcvt_p2
	s_sub_i32 s101, s2, 0x120
	s_sub_i32 s100, s3, 0x120
	s_min_u32 s22, s22, 0x7e0
	s_branch .Lcvt_all
.Lcvt_p2:
	s_add_i32 s101, s2, 0x7e0

; __device__ __forceinline__ void phase_cvt(const Params& p, int l, char* smem) {
;   const int total = p.job_tiles[l];
;   for (int t = blockIdx.x; t < total; t += gridDim.x) {
;     int ji = 0;
; #pragma unroll 1
;     for (int q = 1; q < 15; ++q) if (t >= p.jobs[l * 15 + q].tile0) ji = q;
;     const CvtJob& j = p.jobs[l * 15 + ji];
;     cvt_tile(j, t - j.tile0, smem);
;   }
; }
.Lcvt_exit:
	s_cmp_eq_u32 s100, s3
	s_cbranch_scc1 .LBB0_50
	s_load_dword s22, s[0:1], 0x6a8
	s_mov_b32 s100, s3
	s_add_i32 s101, s2, 0x7e0
	s_waitcnt lgkmcnt(0)
	s_branch .Lcvt_all
